# DA loop: s_setprio 1 around the QK and PV MFMA sections, 0 during softmax
# speedup vs baseline: 1.0238x; 1.0016x over previous
; #define SBAR() __builtin_amdgcn_sched_barrier(0)
; __device__ __forceinline__ void finishSM(f32x16& p0, f32x16& p1, float alpha, float& l_reg, bf16x8& pa0, bf16x8& pa1, bf16x8& pa2, bf16x8& pa3) {
; #pragma unroll
;   for (int r = 0; r < 16; ++r) p1[r] = __builtin_amdgcn_exp2f(p1[r]);
;   float ps = 0;
; #pragma unroll
;   for (int r = 0; r < 16; ++r) ps += p0[r];
; #pragma unroll
;   for (int r = 0; r < 16; ++r) ps += p1[r];
;   { auto rr = __builtin_amdgcn_permlane32_swap(__float_as_uint(ps), __float_as_uint(ps), false, false);
;     ps = __uint_as_float(rr[0]) + __uint_as_float(rr[1]); }
;   l_reg = l_reg * alpha + ps;
;   PK4(p0, 0, pa0); PK4(p0, 8, pa1); PK4(p1, 0, pa2); PK4(p1, 8, pa3);
; }
; __device__ __forceinline__ void partialSM_rc(f32x16& p0, f32x16& p1, float& m_reg, float& mn, float& alpha, float C, float thr, float rc, float pmax) {
;   if (__builtin_expect(__all(pmax - m_reg <= thr), 1)) { mn = m_reg; alpha = 1.f; }
;   else { mn = fmaxf(m_reg, pmax); alpha = __builtin_amdgcn_exp2f((m_reg - mn) * C); m_reg = mn; }
;   const float mnC = (rc - mn) * C;
; #pragma unroll
;   for (int r = 0; r < 16; ++r) p0[r] = fmaf(p0[r], C, mnC);
; #pragma unroll
;   for (int r = 0; r < 16; ++r) p1[r] = fmaf(p1[r], C, mnC);
; #pragma unroll
;   for (int r = 0; r < 16; ++r) p0[r] = __builtin_amdgcn_exp2f(p0[r]);
; }
; template <int D0> __device__ __forceinline__ void pv_one_lean(f32x16& od, int vb, bf16x8 pa0, bf16x8 pa1, bf16x8 pa2, bf16x8 pa3) {
;     ...
;   { const s16x4 l0 = tr_read<v_rd_off(D0, 0, 0)>(vb), h0 = tr_read<v_rd_off(D0, 0, 1)>(vb), l1 = tr_read<v_rd_off(D0, 1, 0)>(vb), h1 = tr_read<v_rd_off(D0, 1, 1)>(vb);
;     asm volatile("s_waitcnt lgkmcnt(0)" ::: "memory"); SBAR();
;     od = __builtin_amdgcn_mfma_f32_32x32x16_bf16(pa0, PKL(l0, h0), od, 0, 0, 0); od = __builtin_amdgcn_mfma_f32_32x32x16_bf16(pa1, PKL(l1, h1), od, 0, 0, 0); }
;   SBAR();
;   { const s16x4 l2 = tr_read<v_rd_off(D0, 2, 0)>(vb), h2 = tr_read<v_rd_off(D0, 2, 1)>(vb), l3 = tr_read<v_rd_off(D0, 3, 0)>(vb), h3 = tr_read<v_rd_off(D0, 3, 1)>(vb);
;     asm volatile("s_waitcnt lgkmcnt(0)" ::: "memory"); SBAR();
;     od = __builtin_amdgcn_mfma_f32_32x32x16_bf16(pa2, PKL(l2, h2), od, 0, 0, 0); od = __builtin_amdgcn_mfma_f32_32x32x16_bf16(pa3, PKL(l3, h3), od, 0, 0, 0); }
;     ...
; }
; __device__ __forceinline__ void pv_d0_lean(f32x16* o, int vb, bf16x8 pa0, bf16x8 pa1, bf16x8 pa2, bf16x8 pa3) {
.LBB0_1936:
	v_cndmask_b32_e64 v238, v241, v238, s[4:5]
	v_sub_f32_e32 v0, v0, v238
	v_mul_f32_e32 v0, 0x3e0293ee, v0
	v_fmamk_f32 v146, v146, 0x3e0293ee, v0
	v_fmamk_f32 v147, v147, 0x3e0293ee, v0
	v_exp_f32_e32 v146, v146
	v_fmamk_f32 v148, v148, 0x3e0293ee, v0
	v_exp_f32_e32 v147, v147
	v_fmamk_f32 v149, v149, 0x3e0293ee, v0
	v_exp_f32_e32 v148, v148
	v_fmamk_f32 v150, v150, 0x3e0293ee, v0
	v_exp_f32_e32 v149, v149
	v_fmamk_f32 v151, v151, 0x3e0293ee, v0
	v_fmamk_f32 v152, v152, 0x3e0293ee, v0
	v_fmamk_f32 v153, v153, 0x3e0293ee, v0
	v_fmamk_f32 v154, v154, 0x3e0293ee, v0
	v_fmamk_f32 v155, v155, 0x3e0293ee, v0
	v_fmamk_f32 v156, v156, 0x3e0293ee, v0
	v_fmamk_f32 v157, v157, 0x3e0293ee, v0
	v_fmamk_f32 v158, v158, 0x3e0293ee, v0
	v_fmamk_f32 v159, v159, 0x3e0293ee, v0
	v_fmamk_f32 v160, v160, 0x3e0293ee, v0
	v_fmamk_f32 v161, v161, 0x3e0293ee, v0
	v_fmamk_f32 v162, v162, 0x3e0293ee, v0
	v_fmamk_f32 v163, v163, 0x3e0293ee, v0
	v_fmamk_f32 v164, v164, 0x3e0293ee, v0
	v_fmamk_f32 v165, v165, 0x3e0293ee, v0
	v_fmamk_f32 v166, v166, 0x3e0293ee, v0
	v_fmamk_f32 v167, v167, 0x3e0293ee, v0
	v_fmamk_f32 v168, v168, 0x3e0293ee, v0
	v_fmamk_f32 v169, v169, 0x3e0293ee, v0
	v_fmamk_f32 v170, v170, 0x3e0293ee, v0
	v_fmamk_f32 v171, v171, 0x3e0293ee, v0
	v_fmamk_f32 v172, v172, 0x3e0293ee, v0
	v_fmamk_f32 v173, v173, 0x3e0293ee, v0
	v_fmamk_f32 v174, v174, 0x3e0293ee, v0
	v_fmamk_f32 v175, v175, 0x3e0293ee, v0
	v_fmamk_f32 v176, v176, 0x3e0293ee, v0
	v_fmac_f32_e32 v0, 0x3e0293ee, v177
	v_exp_f32_e32 v150, v150
	v_add_f32_e32 v177, 0, v146
	v_exp_f32_e32 v151, v151
	v_add_f32_e32 v177, v147, v177
	v_exp_f32_e32 v152, v152
	v_add_f32_e32 v177, v148, v177
	v_exp_f32_e32 v153, v153
	v_add_f32_e32 v177, v149, v177
	v_exp_f32_e32 v154, v154
	v_add_f32_e32 v177, v150, v177
	v_exp_f32_e32 v155, v155
	v_add_f32_e32 v177, v151, v177
	v_exp_f32_e32 v156, v156
	v_add_f32_e32 v177, v152, v177
	v_exp_f32_e32 v157, v157
	v_add_f32_e32 v177, v153, v177
	v_exp_f32_e32 v158, v158
	v_add_f32_e32 v177, v154, v177
	v_exp_f32_e32 v159, v159
	v_add_f32_e32 v177, v155, v177
	v_exp_f32_e32 v160, v160
	v_add_f32_e32 v177, v156, v177
	v_exp_f32_e32 v161, v161
	v_add_f32_e32 v177, v157, v177
	v_exp_f32_e32 v162, v162
	v_add_f32_e32 v177, v158, v177
	v_exp_f32_e32 v163, v163
	v_add_f32_e32 v177, v159, v177
	v_exp_f32_e32 v164, v164
	v_add_f32_e32 v177, v160, v177
	v_exp_f32_e32 v165, v165
	v_add_f32_e32 v177, v161, v177
	v_exp_f32_e32 v166, v166
	v_add_f32_e32 v177, v162, v177
	v_exp_f32_e32 v167, v167
	v_add_f32_e32 v177, v163, v177
	v_exp_f32_e32 v168, v168
	v_add_f32_e32 v177, v164, v177
	v_exp_f32_e32 v169, v169
	v_add_f32_e32 v177, v165, v177
	v_exp_f32_e32 v170, v170
	v_add_f32_e32 v177, v166, v177
	v_exp_f32_e32 v171, v171
	v_add_f32_e32 v177, v167, v177
	v_exp_f32_e32 v172, v172
	v_add_f32_e32 v177, v168, v177
	v_exp_f32_e32 v173, v173
	v_add_f32_e32 v177, v169, v177
	v_exp_f32_e32 v174, v174
	v_add_f32_e32 v177, v170, v177
	v_exp_f32_e32 v175, v175
	v_add_f32_e32 v177, v171, v177
	v_exp_f32_e32 v176, v176
	v_add_f32_e32 v177, v172, v177
	v_exp_f32_e32 v0, v0
	v_add_f32_e32 v177, v173, v177
	v_add_f32_e32 v177, v174, v177
	v_add_f32_e32 v177, v175, v177
	v_add_f32_e32 v177, v176, v177
	v_add_f32_e32 v177, v0, v177
	v_mov_b32_e32 v210, v177
	s_nop 1
	v_permlane32_swap_b32_e32 v177, v210
	v_add_f32_e32 v177, v177, v210
	v_cvt_pk_bf16_f32 v146, v146, v147
	v_cvt_pk_bf16_f32 v147, v148, v149
	v_cvt_pk_bf16_f32 v148, v150, v151
	v_cvt_pk_bf16_f32 v149, v152, v153
	v_cvt_pk_bf16_f32 v150, v154, v155
	v_cvt_pk_bf16_f32 v151, v156, v157
	v_cvt_pk_bf16_f32 v152, v158, v159
	v_cvt_pk_bf16_f32 v153, v160, v161
	v_cvt_pk_bf16_f32 v154, v162, v163
	v_cvt_pk_bf16_f32 v155, v164, v165
	v_cvt_pk_bf16_f32 v156, v166, v167
	v_cvt_pk_bf16_f32 v157, v168, v169
	v_cvt_pk_bf16_f32 v158, v170, v171
	v_cvt_pk_bf16_f32 v159, v172, v173
	v_cvt_pk_bf16_f32 v160, v174, v175
	v_cvt_pk_bf16_f32 v161, v176, v0
	v_fmac_f32_e32 v177, v240, v229
	v_permlane32_swap_b32_e32 v146, v148
	v_permlane32_swap_b32_e32 v147, v149
	v_permlane32_swap_b32_e32 v150, v152
	v_permlane32_swap_b32_e32 v151, v153
	v_permlane32_swap_b32_e32 v154, v156
	v_permlane32_swap_b32_e32 v155, v157
	v_permlane32_swap_b32_e32 v158, v160
	v_permlane32_swap_b32_e32 v159, v161
	v_mov_b32_e32 v240, v177
	s_setprio 1
	v_lshl_add_u32 v0, s40, 15, v237
	ds_read_b64_tr_b16 v[162:163], v0 offset:0
	ds_read_b64_tr_b16 v[164:165], v0 offset:0x800
	ds_read_b64_tr_b16 v[166:167], v0 offset:0x1000
	ds_read_b64_tr_b16 v[168:169], v0 offset:0x1800
	ds_read_b64_tr_b16 v[170:171], v0 offset:0x2000
	ds_read_b64_tr_b16 v[172:173], v0 offset:0x2800
	ds_read_b64_tr_b16 v[174:175], v0 offset:0x3000
	ds_read_b64_tr_b16 v[176:177], v0 offset:0x3800
	s_waitcnt lgkmcnt(4)
	v_mfma_f32_32x32x16_bf16 v[114:129], v[146:149], v[162:165], v[114:129]
	v_mfma_f32_32x32x16_bf16 v[114:129], v[150:153], v[166:169], v[114:129]
	ds_read_b64_tr_b16 v[162:163], v0 offset:0x200
	ds_read_b64_tr_b16 v[164:165], v0 offset:0xa00
	ds_read_b64_tr_b16 v[166:167], v0 offset:0x1200
	ds_read_b64_tr_b16 v[168:169], v0 offset:0x1a00
	s_waitcnt lgkmcnt(4)
; #define SBAR() __builtin_amdgcn_sched_barrier(0)
; template <int OFF> __device__ __forceinline__ s16x4 tr_read(int vb) { s16x4 r; asm volatile("ds_read_b64_tr_b16 %0, %1 offset:%2" : "=&v"(r) : "v"(vb), "i"(OFF) : "memory"); return r; }
; template <int D0> __device__ __forceinline__ void pv_one_lean(f32x16& od, int vb, bf16x8 pa0, bf16x8 pa1, bf16x8 pa2, bf16x8 pa3) {
;     ...
;   { const s16x4 l0 = tr_read<v_rd_off(D0, 0, 0)>(vb), h0 = tr_read<v_rd_off(D0, 0, 1)>(vb), l1 = tr_read<v_rd_off(D0, 1, 0)>(vb), h1 = tr_read<v_rd_off(D0, 1, 1)>(vb);
;     asm volatile("s_waitcnt lgkmcnt(0)" ::: "memory"); SBAR();
;     od = __builtin_amdgcn_mfma_f32_32x32x16_bf16(pa0, PKL(l0, h0), od, 0, 0, 0); od = __builtin_amdgcn_mfma_f32_32x32x16_bf16(pa1, PKL(l1, h1), od, 0, 0, 0); }
;   SBAR();
;   { const s16x4 l2 = tr_read<v_rd_off(D0, 2, 0)>(vb), h2 = tr_read<v_rd_off(D0, 2, 1)>(vb), l3 = tr_read<v_rd_off(D0, 3, 0)>(vb), h3 = tr_read<v_rd_off(D0, 3, 1)>(vb);
;     asm volatile("s_waitcnt lgkmcnt(0)" ::: "memory"); SBAR();
;     od = __builtin_amdgcn_mfma_f32_32x32x16_bf16(pa2, PKL(l2, h2), od, 0, 0, 0); od = __builtin_amdgcn_mfma_f32_32x32x16_bf16(pa3, PKL(l3, h3), od, 0, 0, 0); }
;     ...
; }
; __device__ __forceinline__ void pv_d0_lean(f32x16* o, int vb, bf16x8 pa0, bf16x8 pa1, bf16x8 pa2, bf16x8 pa3) {
;   pv_one_lean<0>(o[0], vb, pa0, pa1, pa2, pa3); SBAR(); pv_one_lean<1>(o[1], vb, pa0, pa1, pa2, pa3); SBAR(); pv_one_lean<2>(o[2], vb, pa0, pa1, pa2, pa3); SBAR(); pv_one_lean<3>(o[3], vb, pa0, pa1, pa2, pa3);
; }
; __device__ __forceinline__ void attn_unit_da(const AttnUnit& U, char* lds) {
;     ...
;       finishSM(p0, p1, al, l_reg, pa0, pa1, pa2, pa3); SBAR();
;       pv_d0_lean(o, vb0 + st * SHM_V2, pa0, pa1, pa2, pa3); SBAR();
;       pv_d0_lean(o + 4, vb0 + st * SHM_V2 + 16384, pa0, pa1, pa2, pa3);
	v_mfma_f32_32x32x16_bf16 v[114:129], v[154:157], v[170:173], v[114:129]
	v_mfma_f32_32x32x16_bf16 v[114:129], v[158:161], v[174:177], v[114:129]
	ds_read_b64_tr_b16 v[170:171], v0 offset:0x2200
	ds_read_b64_tr_b16 v[172:173], v0 offset:0x2a00
	ds_read_b64_tr_b16 v[174:175], v0 offset:0x3200
	ds_read_b64_tr_b16 v[176:177], v0 offset:0x3a00
	s_waitcnt lgkmcnt(4)
	v_mfma_f32_32x32x16_bf16 v[98:113], v[146:149], v[162:165], v[98:113]
	v_mfma_f32_32x32x16_bf16 v[98:113], v[150:153], v[166:169], v[98:113]
	ds_read_b64_tr_b16 v[162:163], v0 offset:0x400
	ds_read_b64_tr_b16 v[164:165], v0 offset:0xc00
	ds_read_b64_tr_b16 v[166:167], v0 offset:0x1400
	ds_read_b64_tr_b16 v[168:169], v0 offset:0x1c00
	s_waitcnt lgkmcnt(4)
	v_mfma_f32_32x32x16_bf16 v[98:113], v[154:157], v[170:173], v[98:113]
	v_mfma_f32_32x32x16_bf16 v[98:113], v[158:161], v[174:177], v[98:113]
	ds_read_b64_tr_b16 v[170:171], v0 offset:0x2400
	ds_read_b64_tr_b16 v[172:173], v0 offset:0x2c00
	ds_read_b64_tr_b16 v[174:175], v0 offset:0x3400
	ds_read_b64_tr_b16 v[176:177], v0 offset:0x3c00
	s_waitcnt lgkmcnt(4)
	v_mfma_f32_32x32x16_bf16 v[82:97], v[146:149], v[162:165], v[82:97]
	v_mfma_f32_32x32x16_bf16 v[82:97], v[150:153], v[166:169], v[82:97]
	ds_read_b64_tr_b16 v[162:163], v0 offset:0x600
	ds_read_b64_tr_b16 v[164:165], v0 offset:0xe00
	ds_read_b64_tr_b16 v[166:167], v0 offset:0x1600
	ds_read_b64_tr_b16 v[168:169], v0 offset:0x1e00
	s_waitcnt lgkmcnt(4)
	v_mfma_f32_32x32x16_bf16 v[82:97], v[154:157], v[170:173], v[82:97]
	v_mfma_f32_32x32x16_bf16 v[82:97], v[158:161], v[174:177], v[82:97]
	ds_read_b64_tr_b16 v[170:171], v0 offset:0x2600
	ds_read_b64_tr_b16 v[172:173], v0 offset:0x2e00
	ds_read_b64_tr_b16 v[174:175], v0 offset:0x3600
	ds_read_b64_tr_b16 v[176:177], v0 offset:0x3e00
	s_waitcnt lgkmcnt(4)
	v_mfma_f32_32x32x16_bf16 v[66:81], v[146:149], v[162:165], v[66:81]
	v_mfma_f32_32x32x16_bf16 v[66:81], v[150:153], v[166:169], v[66:81]
	v_add_u32_e32 v0, 0x4000, v0
	ds_read_b64_tr_b16 v[162:163], v0 offset:0
	ds_read_b64_tr_b16 v[164:165], v0 offset:0x800
	ds_read_b64_tr_b16 v[166:167], v0 offset:0x1000
	ds_read_b64_tr_b16 v[168:169], v0 offset:0x1800
	s_waitcnt lgkmcnt(4)
	v_mfma_f32_32x32x16_bf16 v[66:81], v[154:157], v[170:173], v[66:81]
	v_mfma_f32_32x32x16_bf16 v[66:81], v[158:161], v[174:177], v[66:81]
	ds_read_b64_tr_b16 v[170:171], v0 offset:0x2000
	ds_read_b64_tr_b16 v[172:173], v0 offset:0x2800
	ds_read_b64_tr_b16 v[174:175], v0 offset:0x3000
	ds_read_b64_tr_b16 v[176:177], v0 offset:0x3800
	s_waitcnt lgkmcnt(4)
	v_mfma_f32_32x32x16_bf16 v[50:65], v[146:149], v[162:165], v[50:65]
	v_mfma_f32_32x32x16_bf16 v[50:65], v[150:153], v[166:169], v[50:65]
	ds_read_b64_tr_b16 v[162:163], v0 offset:0x200
	ds_read_b64_tr_b16 v[164:165], v0 offset:0xa00
	ds_read_b64_tr_b16 v[166:167], v0 offset:0x1200
	ds_read_b64_tr_b16 v[168:169], v0 offset:0x1a00
	s_waitcnt lgkmcnt(4)
	v_mfma_f32_32x32x16_bf16 v[50:65], v[154:157], v[170:173], v[50:65]
	v_mfma_f32_32x32x16_bf16 v[50:65], v[158:161], v[174:177], v[50:65]
	ds_read_b64_tr_b16 v[170:171], v0 offset:0x2200
	ds_read_b64_tr_b16 v[172:173], v0 offset:0x2a00
	ds_read_b64_tr_b16 v[174:175], v0 offset:0x3200
	ds_read_b64_tr_b16 v[176:177], v0 offset:0x3a00
	s_waitcnt lgkmcnt(4)
	v_mfma_f32_32x32x16_bf16 v[34:49], v[146:149], v[162:165], v[34:49]
	v_mfma_f32_32x32x16_bf16 v[34:49], v[150:153], v[166:169], v[34:49]
	ds_read_b64_tr_b16 v[162:163], v0 offset:0x400
	ds_read_b64_tr_b16 v[164:165], v0 offset:0xc00
	ds_read_b64_tr_b16 v[166:167], v0 offset:0x1400
	ds_read_b64_tr_b16 v[168:169], v0 offset:0x1c00
	s_waitcnt lgkmcnt(4)
	v_mfma_f32_32x32x16_bf16 v[34:49], v[154:157], v[170:173], v[34:49]
	v_mfma_f32_32x32x16_bf16 v[34:49], v[158:161], v[174:177], v[34:49]
	ds_read_b64_tr_b16 v[170:171], v0 offset:0x2400
	ds_read_b64_tr_b16 v[172:173], v0 offset:0x2c00
	ds_read_b64_tr_b16 v[174:175], v0 offset:0x3400
	ds_read_b64_tr_b16 v[176:177], v0 offset:0x3c00
	s_waitcnt lgkmcnt(4)
	v_mfma_f32_32x32x16_bf16 v[18:33], v[146:149], v[162:165], v[18:33]
	v_mfma_f32_32x32x16_bf16 v[18:33], v[150:153], v[166:169], v[18:33]
	ds_read_b64_tr_b16 v[162:163], v0 offset:0x600
	ds_read_b64_tr_b16 v[164:165], v0 offset:0xe00
	ds_read_b64_tr_b16 v[166:167], v0 offset:0x1600
	ds_read_b64_tr_b16 v[168:169], v0 offset:0x1e00
	s_waitcnt lgkmcnt(4)
	v_mfma_f32_32x32x16_bf16 v[18:33], v[154:157], v[170:173], v[18:33]
	v_mfma_f32_32x32x16_bf16 v[18:33], v[158:161], v[174:177], v[18:33]
	ds_read_b64_tr_b16 v[170:171], v0 offset:0x2600
	ds_read_b64_tr_b16 v[172:173], v0 offset:0x2e00
	ds_read_b64_tr_b16 v[174:175], v0 offset:0x3600
	ds_read_b64_tr_b16 v[176:177], v0 offset:0x3e00
	s_waitcnt lgkmcnt(4)
	v_mfma_f32_32x32x16_bf16 v[2:17], v[146:149], v[162:165], v[2:17]
	v_mfma_f32_32x32x16_bf16 v[2:17], v[150:153], v[166:169], v[2:17]
	s_waitcnt lgkmcnt(0)
	v_mfma_f32_32x32x16_bf16 v[2:17], v[154:157], v[170:173], v[2:17]
	v_mfma_f32_32x32x16_bf16 v[2:17], v[158:161], v[174:177], v[2:17]
	s_setprio 0

; #define SBAR() __builtin_amdgcn_sched_barrier(0)
; __device__ __forceinline__ int crow(int r, int hi) { return (r & 3) + 8 * (r >> 2) + 4 * hi; }
; template <int DQK> __device__ __forceinline__ void qkt_acc(f32x16& p0, f32x16& p1, const char* Ks, const bf16x8* qr, int r32, int hi) {
;   constexpr int ROWB = DQK * 2;
;   const int sw = (r32 & 7) << 4; const char* k0p = Ks + r32 * ROWB; const char* k1p = Ks + (32 + r32) * ROWB;
; #pragma unroll
;   for (int d0 = 0; d0 < DQK / 16; ++d0) { const int cb = ((d0 * 16 + hi * 8) * 2) ^ sw;
;     const bf16x8 b0 = *reinterpret_cast<const bf16x8*>(k0p + cb);
;     const bf16x8 b1 = *reinterpret_cast<const bf16x8*>(k1p + cb);
;     p0 = __builtin_amdgcn_mfma_f32_32x32x16_bf16(b0, qr[d0], p0, 0, 0, 0);
;     p1 = __builtin_amdgcn_mfma_f32_32x32x16_bf16(b1, qr[d0], p1, 0, 0, 0); }
; }
; __device__ __forceinline__ void attn_unit_da(const AttnUnit& U, char* lds) {
;     ...
;     { const int c_ = __builtin_amdgcn_readfirstlane(cls[j]); const float* ak_ = aux + j * KVBLK;
;       if (c_ < 2) { rc = (c_ == 0) ? pq * U.nsl : -pq * U.nsl;
; #pragma unroll
;         for (int g = 0; g < 4; ++g) { const f32x4 a_ = *(const f32x4*)(ak_ + 8 * g + 4 * hi), b_ = *(const f32x4*)(ak_ + 32 + 8 * g + 4 * hi);
; #pragma unroll
;           for (int e = 0; e < 4; ++e) { p0[4 * g + e] = a_[e]; p1[4 * g + e] = b_[e]; } } }
;       else { rc = 0.f; const int* pg_ = U.posg + j * KVBLK;
; #pragma unroll
;         for (int g = 0; g < 4; ++g)
; #pragma unroll
;           for (int e = 0; e < 4; ++e) { p0[4 * g + e] = fabsf(pq - (float)(pg_[8 * g + 4 * hi + e] - pq0i)) * U.nsl; p1[4 * g + e] = fabsf(pq - (float)(pg_[32 + 8 * g + 4 * hi + e] - pq0i)) * U.nsl; } } }
;     SBAR(); qkt_acc<DQK>(p0, p1, K_lds + st * SHM_K, qr, r32, hi); SBAR();
;     const float pmax = rowmax32(p0, p1) + rc;
;     if (!__all((pmax - m_reg) * U.C < -150.f)) {
;       partialSM_rc(p0, p1, m_reg, mn, al, U.C, U.thr, rc, pmax);
;       if (__any(al < 1.f)) { if (hi == 0) al_l[r32] = al; asm volatile("s_waitcnt lgkmcnt(0)" ::: "memory");
; #pragma unroll
;         for (int d = 0; d < 8; ++d)
; #pragma unroll
;           for (int r = 0; r < 16; ++r) o[d][r] *= al_l[crow(r, hi)]; }
.LBB0_1942:
	s_andn2_b64 vcc, exec, s[4:5]
	v_mov_b32_e32 v0, 0
	s_cbranch_vccnz .LBB0_1944
	v_add_u32_e32 v0, 0, v227
	v_add_u32_e32 v146, 0x18800, v0
	v_add_u32_e32 v150, 0x18880, v0
	ds_read_b128 v[146:149], v146
	ds_read_b128 v[162:165], v150
	v_add_u32_e32 v150, 0x18820, v0
	v_add_u32_e32 v154, 0x188a0, v0
	ds_read_b128 v[150:153], v150
	ds_read_b128 v[166:169], v154
	v_add_u32_e32 v154, 0x18840, v0
	v_add_u32_e32 v158, 0x188c0, v0
	ds_read_b128 v[154:157], v154
	ds_read_b128 v[170:173], v158
	v_add_u32_e32 v158, 0x18860, v0
	v_add_u32_e32 v0, 0x188e0, v0
	ds_read_b128 v[158:161], v158
	ds_read_b128 v[174:177], v0
	s_cmp_eq_u32 s18, 0
	s_cselect_b64 s[4:5], -1, 0
	v_cndmask_b32_e64 v0, -v130, v130, s[4:5]
	v_mul_f32_e32 v0, v228, v0
	s_setprio 1
.LBB0_1944:
	v_lshl_add_u32 v218, s40, 14, v245
	v_add_u32_e32 v214, v218, v246
	ds_read_b128 v[210:213], v214
	ds_read_b128 v[214:217], v214 offset:8192
	s_waitcnt lgkmcnt(1)
	v_mfma_f32_32x32x16_bf16 v[146:161], v[210:213], v[178:181], v[146:161]
	v_add_u32_e32 v210, v218, v247
	ds_read_b128 v[210:213], v210
	s_waitcnt lgkmcnt(1)
	v_mfma_f32_32x32x16_bf16 v[162:177], v[214:217], v[178:181], v[162:177]
	v_add_u32_e32 v214, v218, v247
	ds_read_b128 v[214:217], v214 offset:8192
	s_waitcnt lgkmcnt(1)
	v_mfma_f32_32x32x16_bf16 v[146:161], v[210:213], v[182:185], v[146:161]
	v_add_u32_e32 v210, v218, v248
	ds_read_b128 v[210:213], v210
	s_waitcnt lgkmcnt(1)
	v_mfma_f32_32x32x16_bf16 v[162:177], v[214:217], v[182:185], v[162:177]
	v_add_u32_e32 v214, v218, v248
	ds_read_b128 v[214:217], v214 offset:8192
	s_waitcnt lgkmcnt(1)
	v_mfma_f32_32x32x16_bf16 v[146:161], v[210:213], v[186:189], v[146:161]
	v_add_u32_e32 v210, v218, v249
	ds_read_b128 v[210:213], v210
	s_waitcnt lgkmcnt(1)
	v_mfma_f32_32x32x16_bf16 v[162:177], v[214:217], v[186:189], v[162:177]
	v_add_u32_e32 v214, v218, v249
	ds_read_b128 v[214:217], v214 offset:8192
	s_waitcnt lgkmcnt(1)
	v_mfma_f32_32x32x16_bf16 v[146:161], v[210:213], v[190:193], v[146:161]
	v_add_u32_e32 v210, v218, v250
	ds_read_b128 v[210:213], v210
	s_waitcnt lgkmcnt(1)
	v_mfma_f32_32x32x16_bf16 v[162:177], v[214:217], v[190:193], v[162:177]
	v_add_u32_e32 v214, v218, v250
	ds_read_b128 v[214:217], v214 offset:8192
	s_waitcnt lgkmcnt(1)
	v_mfma_f32_32x32x16_bf16 v[146:161], v[210:213], v[194:197], v[146:161]
	v_add_u32_e32 v210, v218, v252
	ds_read_b128 v[210:213], v210
	s_waitcnt lgkmcnt(1)
	v_mfma_f32_32x32x16_bf16 v[162:177], v[214:217], v[194:197], v[162:177]
	v_add_u32_e32 v214, v218, v252
	ds_read_b128 v[214:217], v214 offset:8192
	s_waitcnt lgkmcnt(1)
	v_mfma_f32_32x32x16_bf16 v[146:161], v[210:213], v[198:201], v[146:161]
	v_add_u32_e32 v210, v218, v253
	ds_read_b128 v[210:213], v210
	s_waitcnt lgkmcnt(1)
	v_mfma_f32_32x32x16_bf16 v[162:177], v[214:217], v[198:201], v[162:177]
	v_add_u32_e32 v214, v218, v253
	ds_read_b128 v[214:217], v214 offset:8192
	s_waitcnt lgkmcnt(1)
	v_mfma_f32_32x32x16_bf16 v[146:161], v[210:213], v[202:205], v[146:161]
	v_add_u32_e32 v210, v218, v254
	ds_read_b128 v[210:213], v210
	s_waitcnt lgkmcnt(1)
	v_mfma_f32_32x32x16_bf16 v[162:177], v[214:217], v[202:205], v[162:177]
	v_add_u32_e32 v214, v218, v254
	ds_read_b128 v[214:217], v214 offset:8192
	s_waitcnt lgkmcnt(1)
	v_mfma_f32_32x32x16_bf16 v[146:161], v[210:213], v[206:209], v[146:161]
	s_setprio 0
	s_waitcnt lgkmcnt(0)
	v_mfma_f32_32x32x16_bf16 v[162:177], v[214:217], v[206:209], v[162:177]
	s_nop 9
	v_max_f32_e32 v210, v147, v147
	v_max_f32_e32 v211, v146, v146
	v_max_f32_e32 v210, v211, v210
	v_max3_f32 v210, v210, v148, v149
	v_max3_f32 v210, v210, v150, v151
	v_max3_f32 v210, v210, v152, v153
	v_max3_f32 v210, v210, v154, v155
	v_max3_f32 v210, v210, v156, v157
	v_max3_f32 v210, v210, v158, v159
	v_max3_f32 v210, v210, v160, v161
	v_max3_f32 v210, v210, v162, v163
	v_max3_f32 v210, v210, v164, v165
	v_max3_f32 v210, v210, v166, v167
	v_max3_f32 v210, v210, v168, v169
	v_max3_f32 v210, v210, v170, v171
	v_max3_f32 v210, v210, v172, v173
	v_max3_f32 v210, v210, v174, v175
	v_max3_f32 v210, v210, v176, v177
	v_mov_b32_e32 v211, v210
	s_nop 1
	v_permlane32_swap_b32_e32 v210, v211
	v_max_f32_e32 v211, v211, v211
	v_max_f32_e32 v210, v210, v210
	v_max_f32_e32 v210, v210, v211
	v_add_f32_e32 v211, v0, v210
	v_sub_f32_e32 v210, v211, v238
	v_mul_f32_e32 v212, 0x3e0293ee, v210
	v_cmp_gt_f32_e32 vcc, s61, v212
	s_cmp_eq_u64 vcc, exec
	s_cbranch_scc1 .LBB0_1937
	v_max_f32_e32 v211, v211, v211
	v_max_f32_e32 v212, v238, v238
	v_max_f32_e32 v241, v212, v211
	v_sub_f32_e32 v211, v238, v241
	v_mul_f32_e32 v211, 0x3e0293ee, v211
	v_exp_f32_e32 v211, v211
	v_cmp_ge_f32_e32 vcc, s62, v210
	s_cmp_eq_u64 vcc, exec
	s_cselect_b64 s[4:5], -1, 0
	v_cndmask_b32_e64 v229, v211, 1.0, s[4:5]
	v_cmp_gt_f32_e32 vcc, 1.0, v229
	s_cbranch_vccz .LBB0_1936
	s_and_saveexec_b64 s[18:19], s[2:3]
	s_cbranch_execz .LBB0_1935
	ds_write_b32 v251, v229 offset:128
	s_branch .LBB0_1935
